# pass3: lower-bound and forget-logit loads hoisted above the unit's first barrier (one exposed latency instead of three)
# baseline (speedup 1.0000x reference)
.LBB0_310:
	v_mov_b32_e32 v26, v208
	s_load_dwordx2 s[98:99], s[66:67], 0x18
	s_lshl_b32 s0, s60, 4
	s_lshl_b32 s1, s60, 6
	s_and_b32 s0, s0, 0xfffff000
	s_and_b32 s6, s1, 0xfc0
	v_ashrrev_i32_e32 v8, 3, v26
	s_or_b32 s2, s0, s6
	v_and_b32_e32 v25, -16, v8
	s_lshl_b32 s1, s60, 1
	v_add_u32_e32 v0, s2, v25
	v_mov_b64_e32 v[2:3], s[38:39]
	s_movk_i32 s7, 0x1c00
	s_and_b32 s3, s1, 0x180
	v_and_b32_e32 v6, 0x7f, v26
	v_mad_i64_i32 v[2:3], s[4:5], v0, s7, v[2:3]
	s_lshl_b32 s12, s3, 1
	v_lshl_add_u64 v[2:3], v[2:3], 0, s[12:13]
	v_lshlrev_b32_e32 v0, 1, v6
	v_lshl_add_u64 v[2:3], v[2:3], 0, v[0:1]
	s_movk_i32 s1, 0x1000
	v_add_co_u32_e32 v4, vcc, s1, v2
	s_movk_i32 s1, 0x3000
	s_nop 0
	v_addc_co_u32_e32 v5, vcc, 0, v3, vcc
	v_add_co_u32_e32 v10, vcc, s1, v2
	s_movk_i32 s1, 0x5000
	s_nop 0
	v_addc_co_u32_e32 v11, vcc, 0, v3, vcc
	v_add_co_u32_e32 v12, vcc, s1, v2
	s_movk_i32 s1, 0x7000
	s_nop 0
	v_addc_co_u32_e32 v13, vcc, 0, v3, vcc
	v_add_co_u32_e32 v14, vcc, s1, v2
	s_mov_b32 s1, 0xa000
	s_nop 0
	v_addc_co_u32_e32 v15, vcc, 0, v3, vcc
	v_add_co_u32_e32 v16, vcc, s18, v2
	v_ashrrev_i32_e32 v96, 7, v26
	s_nop 0
	v_addc_co_u32_e32 v17, vcc, 0, v3, vcc
	v_add_co_u32_e32 v18, vcc, s1, v2
	s_mov_b32 s1, 0xc000
	s_nop 0
	v_addc_co_u32_e32 v19, vcc, 0, v3, vcc
	v_add_co_u32_e32 v28, vcc, s1, v2
	s_mov_b32 s1, 0xe000
	s_nop 0
	v_addc_co_u32_e32 v29, vcc, 0, v3, vcc
	global_load_ushort v27, v[2:3], off
	global_load_ushort v24, v[4:5], off offset:3072
	global_load_ushort v23, v[10:11], off offset:2048
	global_load_ushort v22, v[12:13], off offset:1024
	global_load_ushort v21, v[14:15], off
	global_load_ushort v20, v[16:17], off offset:3072
	s_nop 0
	global_load_ushort v19, v[18:19], off offset:2048
	s_nop 0
	global_load_ushort v18, v[28:29], off offset:1024
	v_add_co_u32_e32 v4, vcc, s1, v2
	s_mov_b32 s1, 0xf000
	s_nop 0
	v_addc_co_u32_e32 v5, vcc, 0, v3, vcc
	v_add_co_u32_e32 v10, vcc, s1, v2
	s_mov_b32 s1, 0x11000
	s_nop 0
	v_addc_co_u32_e32 v11, vcc, 0, v3, vcc
	v_add_co_u32_e32 v12, vcc, s1, v2
	s_mov_b32 s1, 0x13000
	s_nop 0
	v_addc_co_u32_e32 v13, vcc, 0, v3, vcc
	v_add_co_u32_e32 v28, vcc, s1, v2
	s_mov_b32 s1, 0x15000
	s_nop 0
	v_addc_co_u32_e32 v29, vcc, 0, v3, vcc
	v_add_co_u32_e32 v30, vcc, s1, v2
	s_mov_b32 s1, 0x16000
	s_nop 0
	v_addc_co_u32_e32 v31, vcc, 0, v3, vcc
	v_add_co_u32_e32 v32, vcc, s1, v2
	s_mov_b32 s1, 0x1a000
	s_nop 0
	v_addc_co_u32_e32 v33, vcc, 0, v3, vcc
	v_add_co_u32_e32 v34, vcc, s20, v2
	v_and_b32_e32 v97, 31, v26
	s_nop 0
	v_addc_co_u32_e32 v35, vcc, 0, v3, vcc
	v_add_co_u32_e32 v2, vcc, s1, v2
	s_ashr_i32 s61, s60, 31
	v_lshlrev_b32_e32 v88, 5, v96
	v_addc_co_u32_e32 v3, vcc, 0, v3, vcc
	global_load_ushort v17, v[4:5], off
	global_load_ushort v16, v[10:11], off offset:3072
	global_load_ushort v15, v[12:13], off offset:2048
	global_load_ushort v14, v[28:29], off offset:1024
	s_nop 0
	global_load_ushort v13, v[30:31], off
	global_load_ushort v11, v[32:33], off offset:3072
	global_load_ushort v10, v[34:35], off offset:2048
	global_load_ushort v9, v[2:3], off offset:1024
	s_lshl_b64 s[4:5], s[60:61], 15
	v_or_b32_e32 v2, v88, v97
	s_add_u32 s4, s8, s4
	v_ashrrev_i32_e32 v3, 31, v2
	v_bfe_u32 v98, v26, 5, 1
	s_addc_u32 s5, s9, s5
	v_lshlrev_b64 v[2:3], 8, v[2:3]
	v_lshl_add_u64 v[2:3], s[4:5], 0, v[2:3]
	v_lshlrev_b32_e32 v94, 4, v98
	v_mov_b32_e32 v95, v1
	v_lshl_add_u64 v[30:31], v[2:3], 0, v[94:95]
	v_add_u32_e32 v7, s3, v88
	global_load_dwordx4 v[2:5], v[30:31], off
	global_load_dwordx4 v[78:81], v[30:31], off offset:32
	global_load_dwordx4 v[74:77], v[30:31], off offset:64
	global_load_dwordx4 v[70:73], v[30:31], off offset:96
	global_load_dwordx4 v[44:47], v[30:31], off offset:128
	global_load_dwordx4 v[40:43], v[30:31], off offset:160
	global_load_dwordx4 v[36:39], v[30:31], off offset:192
	global_load_dwordx4 v[66:69], v[30:31], off offset:224
	v_or_b32_e32 v30, v7, v97
	v_ashrrev_i32_e32 v31, 31, v30
	v_lshlrev_b64 v[30:31], 15, v[30:31]
	v_lshl_add_u64 v[30:31], s[44:45], 0, v[30:31]
	s_ashr_i32 s1, s0, 31
	v_lshl_add_u64 v[30:31], s[0:1], 1, v[30:31]
	s_lshl_b32 s0, s6, 1
	s_mov_b32 s1, s13
	v_lshlrev_b32_e32 v28, 3, v98
	v_mov_b32_e32 v29, v1
	v_bfe_u32 v34, v26, 6, 1
	v_lshl_add_u64 v[30:31], v[30:31], 0, s[0:1]
	v_lshl_add_u64 v[30:31], v[30:31], 0, v[28:29]
	v_lshlrev_b32_e32 v95, 5, v34
	v_lshlrev_b32_e32 v32, 6, v34
	v_mov_b32_e32 v33, v1
	v_lshl_add_u64 v[32:33], v[30:31], 0, v[32:33]
	v_or_b32_e32 v99, v95, v97
	global_load_dwordx2 v[62:63], v[32:33], off
	global_load_dwordx2 v[64:65], v[32:33], off offset:16
	global_load_dwordx2 v[54:55], v[32:33], off offset:32
	global_load_dwordx2 v[56:57], v[32:33], off offset:48
	global_load_dwordx2 v[58:59], v[30:31], off
	global_load_dwordx2 v[60:61], v[30:31], off offset:16
	global_load_dwordx2 v[50:51], v[30:31], off offset:32
	global_load_dwordx2 v[52:53], v[30:31], off offset:48
	v_or_b32_e32 v92, s2, v99
	v_mov_b64_e32 v[30:31], s[78:79]
	v_mad_i64_i32 v[30:31], s[0:1], v92, s7, v[30:31]
	v_lshl_add_u64 v[30:31], v[30:31], 0, s[12:13]
	v_ashrrev_i32_e32 v89, 31, v88
	v_lshl_add_u64 v[30:31], v[88:89], 1, v[30:31]
	v_lshl_add_u64 v[28:29], v[30:31], 0, v[28:29]
	s_mov_b64 s[0:1], 0x10d00800
	v_lshl_add_u64 v[30:31], v[28:29], 0, s[0:1]
	v_add_co_u32_e32 v28, vcc, 0x10d00000, v28
	s_mov_b64 s[52:53], s[12:13]
	s_nop 0
	v_addc_co_u32_e32 v29, vcc, 0, v29, vcc
	global_load_dwordx2 v[90:91], v[28:29], off offset:2048
	global_load_dwordx2 v[86:87], v[30:31], off offset:16
	global_load_dwordx2 v[84:85], v[30:31], off offset:32
	global_load_dwordx2 v[82:83], v[30:31], off offset:48
	s_waitcnt lgkmcnt(0)
	v_or_b32_e32 v132, s3, v6
	v_lshlrev_b32_e32 v132, 2, v132
	global_load_dword v186, v132, s[98:99]
	global_load_dword v187, v132, s[98:99] offset:2048
	v_lshl_add_u32 v133, v96, 4, s2
	v_mov_b64_e32 v[134:135], s[78:79]
	v_mad_i64_i32 v[134:135], s[0:1], v133, s7, v[134:135]
	v_lshl_add_u64 v[134:135], v[134:135], 0, s[52:53]
	v_lshl_add_u64 v[134:135], v[134:135], 0, v[0:1]
	s_mov_b64 s[0:1], 0x10d01200
	v_lshl_add_u64 v[134:135], v[134:135], 0, s[0:1]
	s_mov_b64 s[0:1], 0x3800
	global_load_ushort v170, v[134:135], off offset:-3584
	global_load_ushort v171, v[134:135], off offset:3584
	v_lshl_add_u64 v[136:137], v[134:135], 0, s[0:1]
	global_load_ushort v172, v[136:137], off offset:-3584
	global_load_ushort v173, v[136:137], off offset:3584
	v_lshl_add_u64 v[134:135], v[136:137], 0, s[0:1]
	global_load_ushort v174, v[134:135], off offset:-3584
	global_load_ushort v175, v[134:135], off offset:3584
	v_lshl_add_u64 v[136:137], v[134:135], 0, s[0:1]
	global_load_ushort v176, v[136:137], off offset:-3584
	global_load_ushort v177, v[136:137], off offset:3584
	v_lshl_add_u64 v[134:135], v[136:137], 0, s[0:1]
	global_load_ushort v178, v[134:135], off offset:-3584
	global_load_ushort v179, v[134:135], off offset:3584
	v_lshl_add_u64 v[136:137], v[134:135], 0, s[0:1]
	global_load_ushort v180, v[136:137], off offset:-3584
	global_load_ushort v181, v[136:137], off offset:3584
	v_lshl_add_u64 v[134:135], v[136:137], 0, s[0:1]
	global_load_ushort v182, v[134:135], off offset:-3584
	global_load_ushort v183, v[134:135], off offset:3584
	v_lshl_add_u64 v[136:137], v[134:135], 0, s[0:1]
	global_load_ushort v184, v[136:137], off offset:-3584
	global_load_ushort v185, v[136:137], off offset:3584
	s_andn2_b64 vcc, exec, s[30:31]
	v_mov_b32_e32 v7, 0
	s_barrier
	s_cbranch_vccnz .LBB0_312
	s_waitcnt vmcnt(0) lgkmcnt(0)
	v_sub_f32_e32 v7, v186, v187
	v_mul_f32_e32 v7, 0x3fb8aa3b, v7
	v_exp_f32_e32 v7, v7
	s_nop 0
	v_add_f32_e32 v7, 1.0, v7
	v_div_scale_f32 v12, s[0:1], v7, v7, 1.0
	v_rcp_f32_e32 v28, v12
	v_div_scale_f32 v29, vcc, 1.0, v7, 1.0
	v_fma_f32 v30, -v12, v28, 1.0
	v_fmac_f32_e32 v28, v30, v28
	v_mul_f32_e32 v30, v29, v28
	v_fma_f32 v31, -v12, v30, v29
	v_fmac_f32_e32 v30, v31, v28
	v_fma_f32 v12, -v12, v30, v29
	v_div_fmas_f32 v12, v12, v28, v30
	v_div_fixup_f32 v7, v12, v7, 1.0
.LBB0_312:
	v_sub_f32_e32 v12, 1.0, v7
	s_mov_b64 s[0:1], -1
	s_waitcnt vmcnt(0)
	v_mov_b32_e32 v28, v170
	v_mov_b32_e32 v29, v171
	v_mov_b32_e32 v30, v172
	v_mov_b32_e32 v31, v173
	v_mov_b32_e32 v32, v174
	v_mov_b32_e32 v33, v175
	v_mov_b32_e32 v35, v176
	v_mov_b32_e32 v48, v177
	v_mov_b32_e32 v49, v178
	v_mov_b32_e32 v101, v179
	v_mov_b32_e32 v102, v180
	v_mov_b32_e32 v103, v181
	v_mov_b32_e32 v104, v182
	v_mov_b32_e32 v105, v183
	v_mov_b32_e32 v106, v184
	v_mov_b32_e32 v93, v185
	v_lshlrev_b32_e32 v107, 16, v28
	v_mul_f32_e64 v28, |v107|, s47
	v_exp_f32_e32 v28, v28
	v_cmp_le_f32_e32 vcc, 0, v107
	v_add_f32_e32 v108, 1.0, v28
	v_rcp_f32_e32 v100, v108
	s_nop 0
	v_mul_f32_e32 v28, v28, v100
	v_cndmask_b32_e32 v28, v28, v100, vcc
	s_and_b64 vcc, exec, s[36:37]
	s_cbranch_vccz .LBB0_314
	v_fma_f32 v100, v12, v28, v7
	v_cmp_gt_f32_e32 vcc, s35, v100
	s_mov_b32 s0, 0x7f800000
	s_nop 0
	v_cndmask_b32_e64 v109, 0, 32, vcc
	v_ldexp_f32 v100, v100, v109
	v_log_f32_e32 v100, v100
	v_cndmask_b32_e32 v109, 0, v212, vcc
	v_mul_f32_e32 v110, 0x3f317217, v100
	v_fma_f32 v110, v100, s24, -v110
	v_fmac_f32_e32 v110, 0x3377d1cf, v100
	v_fmac_f32_e32 v110, 0x3f317217, v100
	v_cmp_lt_f32_e64 vcc, |v100|, s0
	s_mov_b64 s[0:1], 0
	s_nop 0
	v_cndmask_b32_e32 v100, v100, v110, vcc
	v_sub_f32_e32 v100, v100, v109
